# speedup vs baseline: 1.0318x; 1.0115x over previous
; #define KSWZ(row, colB) ((row) * 256 + ((colB) ^ (KSWZF(row) << 4)))
; #define SBAR() __builtin_amdgcn_sched_barrier(0)
; template <int H> __device__ __forceinline__ void qkt_half(f32x16& pz, const char* Ks, const bf16x8* qr, int r32, int hi) {
;   bf16x8 kf[8];
; #pragma unroll
;   for (int d0 = 0; d0 < 8; ++d0) { const int cb = (d0 * 16 + hi * 8) * 2; kf[d0] = *reinterpret_cast<const bf16x8*>(Ks + KSWZ(32 * H + r32, cb)); }
;   asm volatile("s_waitcnt lgkmcnt(0)" ::: "memory"); SBAR();
;   f32x16 pb = {};
; #pragma unroll
;   for (int d0 = 0; d0 < 8; d0 += 2) {
;     pz = __builtin_amdgcn_mfma_f32_32x32x16_bf16(kf[d0], qr[d0], pz, 0, 0, 0);
;     pb = __builtin_amdgcn_mfma_f32_32x32x16_bf16(kf[d0 + 1], qr[d0 + 1], pb, 0, 0, 0); }
; #pragma unroll
;   for (int r = 0; r < 16; ++r) pz[r] += pb[r];
; }
; template <int MODE>
; __device__ __forceinline__ void nsa_single(const Params& p, const LaneId& L, int q0, int g, int ntiles, int first, char* smem, const bf16x8* qr, float gate, f32x16* o) {
;     ...
;     int pb = row, lo, hl; float badd = 0.f;
;     if (MODE == 1) { const int j = row >> 6; lo = NEG; const bool fl = ((mysel[j >> 5] >> (j & 31)) & 1u) != 0u;
;       if (row == q0) hl = fl ? (L.tq - pb) : NEG; else { hl = 1000; badd = fl ? 0.f : -INFINITY; } }
;     else { lo = L.tq - 512 - pb; hl = L.tq - pb; }
;     constexpr float C = 0.08838834764831845f * LOG2E;
;     const float A1 = L.sl2; const float B1 = L.sl2 * (float)(pb - L.tq) + A1 * (float)(4 * L.hi) + badd;
;     const int lo2 = lo - 4 * L.hi, hl2 = hl - 4 * L.hi;
;     const bool nomask = __all(lo2 < 0 && hl2 >= 63);
.LBB0_318:
	s_ashr_i32 s3, s2, 5
	v_lshl_add_u32 v68, s3, 2, v149
	ds_read_b32 v72, v68
	s_lshl_b32 s3, s2, 6
	s_and_b32 s2, s2, 31
	v_sub_u32_e32 v74, s3, v148
	v_cvt_f32_i32_e32 v74, v74
	s_waitcnt lgkmcnt(0)
	v_bfe_u32 v72, v72, s2, 1
	s_cmp_eq_u32 s3, s5
	v_subrev_u32_e32 v73, s3, v148
	v_cmp_eq_u32_e32 vcc, 0, v72
	v_fma_f32 v74, v138, v74, v151
	s_nop 1
	v_cndmask_b32_e32 v72, v73, v190, vcc
	v_cndmask_b32_e32 v73, 0, v183, vcc
	s_cselect_b64 vcc, -1, 0
	v_cndmask_b32_e32 v72, v191, v72, vcc
	v_cndmask_b32_e64 v73, v73, 0, vcc
	v_sub_u32_e32 v163, v72, v150
	v_add_f32_e32 v140, v74, v73
	v_cmp_lt_i32_e32 vcc, 62, v163
	s_nop 3
	s_cmp_lg_u64 vcc, exec
	s_cselect_b64 s[98:99], -1, 0
	v_add_u32_e32 v242, s22, v152
	v_add_u32_e32 v248, s22, v161
	v_add_u32_e32 v249, v242, v153
	ds_read_b128 v[84:87], v249
	v_add_u32_e32 v251, v242, v154
	ds_read_b128 v[88:91], v251
	v_add_u32_e32 v249, v242, v155
	ds_read_b128 v[92:95], v249
	v_add_u32_e32 v251, v242, v156
	ds_read_b128 v[96:99], v251
	v_add_u32_e32 v249, v242, v157
	ds_read_b128 v[194:197], v249
	v_add_u32_e32 v251, v242, v158
	ds_read_b128 v[198:201], v251
	v_add_u32_e32 v249, v242, v159
	ds_read_b128 v[202:205], v249
	v_add_u32_e32 v251, v242, v160
	ds_read_b128 v[206:209], v251
	v_add_f32_e32 v243, 0x41000000, v165
	v_mov_b32_e32 v250, v140
	s_waitcnt lgkmcnt(7)
	v_mfma_f32_32x32x16_bf16 v[68:83], v[84:87], v[100:103], v[226:241]
	v_add_u32_e32 v249, v242, v153
	ds_read_b128 v[84:87], v249 offset:8192
	s_waitcnt lgkmcnt(7)
	v_mfma_f32_32x32x16_bf16 v[68:83], v[88:91], v[104:107], v[68:83]
	v_add_u32_e32 v251, v242, v154
	ds_read_b128 v[88:91], v251 offset:8192
	s_waitcnt lgkmcnt(7)
	v_mfma_f32_32x32x16_bf16 v[68:83], v[92:95], v[108:111], v[68:83]
	v_add_u32_e32 v249, v242, v155
	ds_read_b128 v[92:95], v249 offset:8192
	s_waitcnt lgkmcnt(7)
	v_mfma_f32_32x32x16_bf16 v[68:83], v[96:99], v[112:115], v[68:83]
	v_add_u32_e32 v251, v242, v156
	ds_read_b128 v[96:99], v251 offset:8192
	s_waitcnt lgkmcnt(7)
	v_mfma_f32_32x32x16_bf16 v[68:83], v[194:197], v[116:119], v[68:83]
	v_add_u32_e32 v249, v242, v157
	ds_read_b128 v[194:197], v249 offset:8192
	s_waitcnt lgkmcnt(7)
	v_mfma_f32_32x32x16_bf16 v[68:83], v[198:201], v[120:123], v[68:83]
	v_add_u32_e32 v251, v242, v158
	ds_read_b128 v[198:201], v251 offset:8192
	s_waitcnt lgkmcnt(7)
	v_mfma_f32_32x32x16_bf16 v[68:83], v[202:205], v[124:127], v[68:83]
	v_add_u32_e32 v249, v242, v159
	ds_read_b128 v[202:205], v249 offset:8192
	s_waitcnt lgkmcnt(7)
	v_mfma_f32_32x32x16_bf16 v[68:83], v[206:209], v[128:131], v[68:83]
	v_add_u32_e32 v251, v242, v160
	ds_read_b128 v[206:209], v251 offset:8192
	s_waitcnt lgkmcnt(7)
	v_mfma_f32_32x32x16_bf16 v[210:225], v[84:87], v[100:103], v[226:241]
	ds_read_b64_tr_b16 v[84:85], v248 offset:0
	ds_read_b64_tr_b16 v[86:87], v248 offset:2048
	s_waitcnt lgkmcnt(8)
	v_mfma_f32_32x32x16_bf16 v[210:225], v[88:91], v[104:107], v[210:225]
	ds_read_b64_tr_b16 v[88:89], v248 offset:4096
	ds_read_b64_tr_b16 v[90:91], v248 offset:6144
	s_waitcnt lgkmcnt(9)
	v_mfma_f32_32x32x16_bf16 v[210:225], v[92:95], v[108:111], v[210:225]
	ds_read_b64_tr_b16 v[92:93], v248 offset:512
	ds_read_b64_tr_b16 v[94:95], v248 offset:2560
	s_waitcnt lgkmcnt(10)
	v_mfma_f32_32x32x16_bf16 v[210:225], v[96:99], v[112:115], v[210:225]
	ds_read_b64_tr_b16 v[96:97], v248 offset:4608
	ds_read_b64_tr_b16 v[98:99], v248 offset:6656
	s_waitcnt lgkmcnt(11)
	v_mfma_f32_32x32x16_bf16 v[210:225], v[194:197], v[116:119], v[210:225]
	ds_read_b64_tr_b16 v[194:195], v248 offset:1024
	ds_read_b64_tr_b16 v[196:197], v248 offset:3072
	s_waitcnt lgkmcnt(12)
	v_mfma_f32_32x32x16_bf16 v[210:225], v[198:201], v[120:123], v[210:225]
	ds_read_b64_tr_b16 v[198:199], v248 offset:5120
	ds_read_b64_tr_b16 v[200:201], v248 offset:7168
	s_waitcnt lgkmcnt(13)
	v_mfma_f32_32x32x16_bf16 v[210:225], v[202:205], v[124:127], v[210:225]
	ds_read_b64_tr_b16 v[202:203], v248 offset:1536
	ds_read_b64_tr_b16 v[204:205], v248 offset:3584
	s_waitcnt lgkmcnt(14)
	v_mfma_f32_32x32x16_bf16 v[210:225], v[206:209], v[128:131], v[210:225]
	ds_read_b64_tr_b16 v[206:207], v248 offset:5632
	ds_read_b64_tr_b16 v[208:209], v248 offset:7680
	v_fmamk_f32 v251, v138, 0x42000000, v140
	s_and_b64 vcc, exec, s[98:99]
	s_cbranch_vccz .Lsel_nm
	v_cmp_lt_i32_e32 vcc, -1, v163
	v_cmp_lt_i32_e64 s[10:11], 0, v163
	v_cmp_lt_i32_e64 s[12:13], 1, v163
	v_cmp_lt_i32_e64 s[2:3], 2, v163
	s_nop 0
	v_cndmask_b32_e32 v68, v183, v68, vcc
	v_cndmask_b32_e64 v69, v183, v69, s[10:11]
	v_cndmask_b32_e64 v70, v183, v70, s[12:13]
	v_cndmask_b32_e64 v71, v183, v71, s[2:3]
	v_cmp_lt_i32_e32 vcc, 7, v163
	v_cmp_lt_i32_e64 s[10:11], 8, v163
	v_cmp_lt_i32_e64 s[12:13], 9, v163
	v_cmp_lt_i32_e64 s[2:3], 10, v163
	s_nop 0
	v_cndmask_b32_e32 v72, v183, v72, vcc
	v_cndmask_b32_e64 v73, v183, v73, s[10:11]
	v_cndmask_b32_e64 v74, v183, v74, s[12:13]
	v_cndmask_b32_e64 v75, v183, v75, s[2:3]
	v_cmp_lt_i32_e32 vcc, 15, v163
	v_cmp_lt_i32_e64 s[10:11], 16, v163
	v_cmp_lt_i32_e64 s[12:13], 17, v163
	v_cmp_lt_i32_e64 s[2:3], 18, v163
	s_nop 0
	v_cndmask_b32_e32 v76, v183, v76, vcc
	v_cndmask_b32_e64 v77, v183, v77, s[10:11]
	v_cndmask_b32_e64 v78, v183, v78, s[12:13]
	v_cndmask_b32_e64 v79, v183, v79, s[2:3]
	v_cmp_lt_i32_e32 vcc, 23, v163
	v_cmp_lt_i32_e64 s[10:11], 24, v163
	v_cmp_lt_i32_e64 s[12:13], 25, v163
	v_cmp_lt_i32_e64 s[2:3], 26, v163
	s_nop 0
	v_cndmask_b32_e32 v80, v183, v80, vcc
	v_cndmask_b32_e64 v81, v183, v81, s[10:11]
	v_cndmask_b32_e64 v82, v183, v82, s[12:13]
	v_cndmask_b32_e64 v83, v183, v83, s[2:3]
	v_cmp_lt_i32_e32 vcc, 31, v163
	v_cmp_lt_i32_e64 s[10:11], 32, v163
	v_cmp_lt_i32_e64 s[12:13], 33, v163
	v_cmp_lt_i32_e64 s[2:3], 34, v163
	s_nop 0
	v_cndmask_b32_e32 v210, v183, v210, vcc
	v_cndmask_b32_e64 v211, v183, v211, s[10:11]
	v_cndmask_b32_e64 v212, v183, v212, s[12:13]
	v_cndmask_b32_e64 v213, v183, v213, s[2:3]
	v_cmp_lt_i32_e32 vcc, 39, v163
	v_cmp_lt_i32_e64 s[10:11], 40, v163
	v_cmp_lt_i32_e64 s[12:13], 41, v163
	v_cmp_lt_i32_e64 s[2:3], 42, v163
	s_nop 0
	v_cndmask_b32_e32 v214, v183, v214, vcc
	v_cndmask_b32_e64 v215, v183, v215, s[10:11]
	v_cndmask_b32_e64 v216, v183, v216, s[12:13]
	v_cndmask_b32_e64 v217, v183, v217, s[2:3]
	v_cmp_lt_i32_e32 vcc, 47, v163
	v_cmp_lt_i32_e64 s[10:11], 48, v163
	v_cmp_lt_i32_e64 s[12:13], 49, v163
	v_cmp_lt_i32_e64 s[2:3], 50, v163
	s_nop 0
	v_cndmask_b32_e32 v218, v183, v218, vcc
	v_cndmask_b32_e64 v219, v183, v219, s[10:11]
	v_cndmask_b32_e64 v220, v183, v220, s[12:13]
	v_cndmask_b32_e64 v221, v183, v221, s[2:3]
	v_cmp_lt_i32_e32 vcc, 55, v163
	v_cmp_lt_i32_e64 s[10:11], 56, v163
	v_cmp_lt_i32_e64 s[12:13], 57, v163
	v_cmp_lt_i32_e64 s[2:3], 58, v163
	s_nop 0
	v_cndmask_b32_e32 v222, v183, v222, vcc
	v_cndmask_b32_e64 v223, v183, v223, s[10:11]
	v_cndmask_b32_e64 v224, v183, v224, s[12:13]
	v_cndmask_b32_e64 v225, v183, v225, s[2:3]
; __device__ __forceinline__ void row_bcast(float* fac, const LaneId& L, float f, f32x4* f4) {
;   if (L.hi == 0) fac[L.r32] = f;
; #pragma unroll
;   for (int a = 0; a < 4; ++a) f4[a] = *reinterpret_cast<const f32x4*>(fac + 8 * a + 4 * L.hi);
; }
.Lsel_nm:
	v_max3_f32 v244, v68, v69, v70
	v_max3_f32 v244, v244, v71, v72
	v_max3_f32 v244, v244, v73, v74
	v_max3_f32 v244, v244, v75, v76
	v_max3_f32 v244, v244, v77, v78
	v_max3_f32 v244, v244, v79, v80
	v_max3_f32 v244, v244, v81, v82
	v_max_f32_e32 v244, v244, v83
	v_fmamk_f32 v246, v244, 0x3e0293ee, v250
	s_nop 1
	v_max3_f32 v244, v210, v211, v212
	v_max3_f32 v244, v244, v213, v214
	v_max3_f32 v244, v244, v215, v216
	v_max3_f32 v244, v244, v217, v218
	v_max3_f32 v244, v244, v219, v220
	v_max3_f32 v244, v244, v221, v222
	v_max3_f32 v244, v244, v223, v224
	v_max_f32_e32 v244, v244, v225
	v_fmamk_f32 v245, v244, 0x3e0293ee, v251
	v_max_f32_e32 v246, v246, v245
	v_mov_b32_e32 v245, v246
	s_nop 1
	v_permlane32_swap_b32_e32 v246, v245
	v_max_f32_e32 v246, v246, v245
	v_cmp_gt_f32_e32 vcc, v246, v243
	s_cbranch_vccz .Lsel_nr
	v_max_f32_e32 v246, v246, v165
	v_sub_f32_e32 v247, v165, v246
	v_exp_f32_e32 v247, v247
	v_mov_b32_e32 v165, v246
	s_and_saveexec_b64 s[2:3], s[8:9]
	ds_write_b32 v147, v247
	s_or_b64 exec, exec, s[2:3]
	v_mul_f32_e32 v162, v162, v247
	ds_read_b128 v[168:171], v146 offset:0
	ds_read_b128 v[172:175], v146 offset:32
	s_waitcnt lgkmcnt(0)
	v_mul_f32_e32 v52, v52, v168
	v_mul_f32_e32 v53, v53, v169
	v_mul_f32_e32 v54, v54, v170
	v_mul_f32_e32 v55, v55, v171
	v_mul_f32_e32 v56, v56, v172
	v_mul_f32_e32 v57, v57, v173
	v_mul_f32_e32 v58, v58, v174
	v_mul_f32_e32 v59, v59, v175
	v_mul_f32_e32 v36, v36, v168
	v_mul_f32_e32 v37, v37, v169
	v_mul_f32_e32 v38, v38, v170
	v_mul_f32_e32 v39, v39, v171
	v_mul_f32_e32 v40, v40, v172
	v_mul_f32_e32 v41, v41, v173
	v_mul_f32_e32 v42, v42, v174
	v_mul_f32_e32 v43, v43, v175
	v_mul_f32_e32 v20, v20, v168
	v_mul_f32_e32 v21, v21, v169
	v_mul_f32_e32 v22, v22, v170
	v_mul_f32_e32 v23, v23, v171
	v_mul_f32_e32 v24, v24, v172
	v_mul_f32_e32 v25, v25, v173
	v_mul_f32_e32 v26, v26, v174
	v_mul_f32_e32 v27, v27, v175
	v_mul_f32_e32 v4, v4, v168
	v_mul_f32_e32 v5, v5, v169
	v_mul_f32_e32 v6, v6, v170
	v_mul_f32_e32 v7, v7, v171
	v_mul_f32_e32 v8, v8, v172
	v_mul_f32_e32 v9, v9, v173
	v_mul_f32_e32 v10, v10, v174
	v_mul_f32_e32 v11, v11, v175
	ds_read_b128 v[168:171], v146 offset:64
	ds_read_b128 v[172:175], v146 offset:96
	s_waitcnt lgkmcnt(0)
	v_mul_f32_e32 v60, v60, v168
	v_mul_f32_e32 v61, v61, v169
	v_mul_f32_e32 v62, v62, v170
	v_mul_f32_e32 v63, v63, v171
	v_mul_f32_e32 v64, v64, v172
	v_mul_f32_e32 v65, v65, v173
	v_mul_f32_e32 v66, v66, v174
	v_mul_f32_e32 v67, v67, v175
	v_mul_f32_e32 v44, v44, v168
	v_mul_f32_e32 v45, v45, v169
	v_mul_f32_e32 v46, v46, v170
	v_mul_f32_e32 v47, v47, v171
	v_mul_f32_e32 v48, v48, v172
	v_mul_f32_e32 v49, v49, v173
	v_mul_f32_e32 v50, v50, v174
	v_mul_f32_e32 v51, v51, v175
	v_mul_f32_e32 v28, v28, v168
	v_mul_f32_e32 v29, v29, v169
	v_mul_f32_e32 v30, v30, v170
	v_mul_f32_e32 v31, v31, v171
	v_mul_f32_e32 v32, v32, v172
	v_mul_f32_e32 v33, v33, v173
	v_mul_f32_e32 v34, v34, v174
	v_mul_f32_e32 v35, v35, v175
	v_mul_f32_e32 v12, v12, v168
	v_mul_f32_e32 v13, v13, v169
	v_mul_f32_e32 v14, v14, v170
	v_mul_f32_e32 v15, v15, v171
	v_mul_f32_e32 v16, v16, v172
	v_mul_f32_e32 v17, v17, v173
	v_mul_f32_e32 v18, v18, v174
	v_mul_f32_e32 v19, v19, v175
; #define SBAR() __builtin_amdgcn_sched_barrier(0)
; #define TRQ(D0) const s16x4 l0_##D0 = tr_read<v_rd_off(D0, 2 * H, 0)>(vb), h0_##D0 = tr_read<v_rd_off(D0, 2 * H, 1)>(vb), \
;                             l1_##D0 = tr_read<v_rd_off(D0, 2 * H + 1, 0)>(vb), h1_##D0 = tr_read<v_rd_off(D0, 2 * H + 1, 1)>(vb)
; template <int H> __device__ __forceinline__ void pv_half(f32x16* o, int vb, bf16x8 paA, bf16x8 paB) {
;     ...
;   TRQ(0); TRQ(1); TRQ(2); TRQ(3);
;     ...
;   asm volatile("s_waitcnt lgkmcnt(0)" ::: "memory"); SBAR();
;     ...
;   o[0] = __builtin_amdgcn_mfma_f32_32x32x16_bf16(paA, PK(l0_0, h0_0), o[0], 0, 0, 0);
;   o[1] = __builtin_amdgcn_mfma_f32_32x32x16_bf16(paA, PK(l0_1, h0_1), o[1], 0, 0, 0);
;   o[2] = __builtin_amdgcn_mfma_f32_32x32x16_bf16(paA, PK(l0_2, h0_2), o[2], 0, 0, 0);
;   o[3] = __builtin_amdgcn_mfma_f32_32x32x16_bf16(paA, PK(l0_3, h0_3), o[3], 0, 0, 0);
;   o[0] = __builtin_amdgcn_mfma_f32_32x32x16_bf16(paB, PK(l1_0, h1_0), o[0], 0, 0, 0);
;   o[1] = __builtin_amdgcn_mfma_f32_32x32x16_bf16(paB, PK(l1_1, h1_1), o[1], 0, 0, 0);
;   o[2] = __builtin_amdgcn_mfma_f32_32x32x16_bf16(paB, PK(l1_2, h1_2), o[2], 0, 0, 0);
;   o[3] = __builtin_amdgcn_mfma_f32_32x32x16_bf16(paB, PK(l1_3, h1_3), o[3], 0, 0, 0);
;     ...
; }
; template <int MODE>
; __device__ __forceinline__ void nsa_single(const Params& p, const LaneId& L, int q0, int g, int ntiles, int first, char* smem, const bf16x8* qr, float gate, f32x16* o) {
;     ...
;     NSA_SHALF(0);
;     NSA_SHALF(1);
.Lsel_nr:
	v_sub_f32_e32 v242, v250, v165
	v_sub_f32_e32 v249, v251, v165
	s_nop 0
	v_fmamk_f32 v68, v68, 0x3e0293ee, v242
	v_fmamk_f32 v69, v69, 0x3e0293ee, v242
	v_fmamk_f32 v70, v70, 0x3e0293ee, v242
	v_fmamk_f32 v71, v71, 0x3e0293ee, v242
	v_fmamk_f32 v72, v72, 0x3e0293ee, v242
	v_fmamk_f32 v73, v73, 0x3e0293ee, v242
	v_fmamk_f32 v74, v74, 0x3e0293ee, v242
	v_fmamk_f32 v75, v75, 0x3e0293ee, v242
	v_fmamk_f32 v76, v76, 0x3e0293ee, v242
	v_fmamk_f32 v77, v77, 0x3e0293ee, v242
	v_fmamk_f32 v78, v78, 0x3e0293ee, v242
	v_fmamk_f32 v79, v79, 0x3e0293ee, v242
	v_fmamk_f32 v80, v80, 0x3e0293ee, v242
	v_fmamk_f32 v81, v81, 0x3e0293ee, v242
	v_fmamk_f32 v82, v82, 0x3e0293ee, v242
	v_fmamk_f32 v83, v83, 0x3e0293ee, v242
	v_exp_f32_e32 v68, v68
	v_exp_f32_e32 v69, v69
	v_exp_f32_e32 v70, v70
	v_exp_f32_e32 v71, v71
	v_exp_f32_e32 v72, v72
	v_exp_f32_e32 v73, v73
	v_exp_f32_e32 v74, v74
	v_exp_f32_e32 v75, v75
	v_exp_f32_e32 v76, v76
	v_exp_f32_e32 v77, v77
	v_exp_f32_e32 v78, v78
	v_exp_f32_e32 v79, v79
	v_exp_f32_e32 v80, v80
	v_exp_f32_e32 v81, v81
	v_exp_f32_e32 v82, v82
	v_exp_f32_e32 v83, v83
	v_fmamk_f32 v210, v210, 0x3e0293ee, v249
	v_fmamk_f32 v211, v211, 0x3e0293ee, v249
	v_fmamk_f32 v212, v212, 0x3e0293ee, v249
	v_fmamk_f32 v213, v213, 0x3e0293ee, v249
	v_fmamk_f32 v214, v214, 0x3e0293ee, v249
	v_fmamk_f32 v215, v215, 0x3e0293ee, v249
	v_fmamk_f32 v216, v216, 0x3e0293ee, v249
	v_fmamk_f32 v217, v217, 0x3e0293ee, v249
	v_fmamk_f32 v218, v218, 0x3e0293ee, v249
	v_fmamk_f32 v219, v219, 0x3e0293ee, v249
	v_fmamk_f32 v220, v220, 0x3e0293ee, v249
	v_fmamk_f32 v221, v221, 0x3e0293ee, v249
	v_fmamk_f32 v222, v222, 0x3e0293ee, v249
	v_fmamk_f32 v223, v223, 0x3e0293ee, v249
	v_fmamk_f32 v224, v224, 0x3e0293ee, v249
	v_fmamk_f32 v225, v225, 0x3e0293ee, v249
	v_add_f32_e32 v246, v68, v69
	v_add_f32_e32 v247, v70, v71
	v_add_f32_e32 v246, v246, v72
	v_add_f32_e32 v246, v246, v73
	v_add_f32_e32 v247, v247, v74
	v_add_f32_e32 v247, v247, v75
	v_add_f32_e32 v246, v246, v76
	v_add_f32_e32 v246, v246, v77
	v_add_f32_e32 v247, v247, v78
	v_add_f32_e32 v247, v247, v79
	v_add_f32_e32 v246, v246, v80
	v_add_f32_e32 v246, v246, v81
	v_add_f32_e32 v247, v247, v82
	v_add_f32_e32 v247, v247, v83
	v_cvt_pk_bf16_f32 v168, v68, v69
	v_cvt_pk_bf16_f32 v169, v70, v71
	v_cvt_pk_bf16_f32 v170, v72, v73
	v_cvt_pk_bf16_f32 v171, v74, v75
	v_cvt_pk_bf16_f32 v172, v76, v77
	v_cvt_pk_bf16_f32 v173, v78, v79
	v_cvt_pk_bf16_f32 v174, v80, v81
	v_cvt_pk_bf16_f32 v175, v82, v83
	v_exp_f32_e32 v210, v210
	v_exp_f32_e32 v211, v211
	v_exp_f32_e32 v212, v212
	v_exp_f32_e32 v213, v213
	v_exp_f32_e32 v214, v214
	v_exp_f32_e32 v215, v215
	v_exp_f32_e32 v216, v216
	v_exp_f32_e32 v217, v217
	v_exp_f32_e32 v218, v218
	v_exp_f32_e32 v219, v219
	v_exp_f32_e32 v220, v220
	v_exp_f32_e32 v221, v221
	v_exp_f32_e32 v222, v222
	v_exp_f32_e32 v223, v223
	v_exp_f32_e32 v224, v224
	v_exp_f32_e32 v225, v225
	v_permlane32_swap_b32_e32 v168, v170
	v_permlane32_swap_b32_e32 v169, v171
	v_permlane32_swap_b32_e32 v172, v174
	v_permlane32_swap_b32_e32 v173, v175
	v_add_f32_e32 v246, v246, v210
	v_add_f32_e32 v246, v246, v211
	v_add_f32_e32 v247, v247, v212
	v_add_f32_e32 v247, v247, v213
	v_add_f32_e32 v246, v246, v214
	v_add_f32_e32 v246, v246, v215
	v_add_f32_e32 v247, v247, v216
	v_add_f32_e32 v247, v247, v217
	v_add_f32_e32 v246, v246, v218
	v_add_f32_e32 v246, v246, v219
	v_add_f32_e32 v247, v247, v220
	v_add_f32_e32 v247, v247, v221
	v_add_f32_e32 v246, v246, v222
	v_add_f32_e32 v246, v246, v223
	v_add_f32_e32 v247, v247, v224
	v_add_f32_e32 v247, v247, v225
	v_add_f32_e32 v246, v246, v247
	v_add_f32_e32 v162, v162, v246
	v_cvt_pk_bf16_f32 v68, v210, v211
	v_cvt_pk_bf16_f32 v69, v212, v213
	v_cvt_pk_bf16_f32 v70, v214, v215
	v_cvt_pk_bf16_f32 v71, v216, v217
	v_cvt_pk_bf16_f32 v72, v218, v219
	v_cvt_pk_bf16_f32 v73, v220, v221
	v_cvt_pk_bf16_f32 v74, v222, v223
	v_cvt_pk_bf16_f32 v75, v224, v225
	s_waitcnt lgkmcnt(0)
	s_nop 0
	v_permlane32_swap_b32_e32 v68, v70
	v_permlane32_swap_b32_e32 v69, v71
	v_permlane32_swap_b32_e32 v72, v74
	v_permlane32_swap_b32_e32 v73, v75
	s_nop 1
	v_mfma_f32_32x32x16_bf16 v[52:67], v[168:171], v[84:87], v[52:67]
	ds_read_b64_tr_b16 v[84:85], v248 offset:8192
	ds_read_b64_tr_b16 v[86:87], v248 offset:10240
	v_mfma_f32_32x32x16_bf16 v[36:51], v[168:171], v[92:95], v[36:51]
	ds_read_b64_tr_b16 v[92:93], v248 offset:8704
	ds_read_b64_tr_b16 v[94:95], v248 offset:10752
	v_mfma_f32_32x32x16_bf16 v[20:35], v[168:171], v[194:197], v[20:35]
	ds_read_b64_tr_b16 v[194:195], v248 offset:9216
	ds_read_b64_tr_b16 v[196:197], v248 offset:11264
	v_mfma_f32_32x32x16_bf16 v[4:19], v[168:171], v[202:205], v[4:19]
	ds_read_b64_tr_b16 v[202:203], v248 offset:9728
	ds_read_b64_tr_b16 v[204:205], v248 offset:11776
	v_mfma_f32_32x32x16_bf16 v[52:67], v[172:175], v[88:91], v[52:67]
	ds_read_b64_tr_b16 v[88:89], v248 offset:12288
	ds_read_b64_tr_b16 v[90:91], v248 offset:14336
	v_mfma_f32_32x32x16_bf16 v[36:51], v[172:175], v[96:99], v[36:51]
	ds_read_b64_tr_b16 v[96:97], v248 offset:12800
	ds_read_b64_tr_b16 v[98:99], v248 offset:14848
	v_mfma_f32_32x32x16_bf16 v[20:35], v[172:175], v[198:201], v[20:35]
	ds_read_b64_tr_b16 v[198:199], v248 offset:13312
	ds_read_b64_tr_b16 v[200:201], v248 offset:15360
	v_mfma_f32_32x32x16_bf16 v[4:19], v[172:175], v[206:209], v[4:19]
	ds_read_b64_tr_b16 v[206:207], v248 offset:13824
	ds_read_b64_tr_b16 v[208:209], v248 offset:15872
	s_waitcnt lgkmcnt(14)
	v_mfma_f32_32x32x16_bf16 v[52:67], v[68:71], v[84:87], v[52:67]
	s_waitcnt lgkmcnt(12)
	v_mfma_f32_32x32x16_bf16 v[36:51], v[68:71], v[92:95], v[36:51]
	s_waitcnt lgkmcnt(10)
	v_mfma_f32_32x32x16_bf16 v[20:35], v[68:71], v[194:197], v[20:35]
	s_waitcnt lgkmcnt(8)
	v_mfma_f32_32x32x16_bf16 v[4:19], v[68:71], v[202:205], v[4:19]
	s_waitcnt lgkmcnt(6)
	v_mfma_f32_32x32x16_bf16 v[52:67], v[72:75], v[88:91], v[52:67]
	s_waitcnt lgkmcnt(4)
	v_mfma_f32_32x32x16_bf16 v[36:51], v[72:75], v[96:99], v[36:51]
	s_waitcnt lgkmcnt(2)
	v_mfma_f32_32x32x16_bf16 v[20:35], v[72:75], v[198:201], v[20:35]
	s_waitcnt lgkmcnt(0)
	v_mfma_f32_32x32x16_bf16 v[4:19], v[72:75], v[206:209], v[4:19]
	s_add_i32 s26, s26, -1
	s_add_i32 s61, s61, 1
	s_addk_i32 s97, 0x4000
	s_cmp_eq_u32 s26, 0
	s_cbranch_scc1 .LBB0_335
	s_branch .LBB0_316

; #define KSWZ(row, colB) ((row) * 256 + ((colB) ^ (KSWZF(row) << 4)))
; #define SBAR() __builtin_amdgcn_sched_barrier(0)
; template <int H> __device__ __forceinline__ void qkt_half(f32x16& pz, const char* Ks, const bf16x8* qr, int r32, int hi) {
;   bf16x8 kf[8];
; #pragma unroll
;   for (int d0 = 0; d0 < 8; ++d0) { const int cb = (d0 * 16 + hi * 8) * 2; kf[d0] = *reinterpret_cast<const bf16x8*>(Ks + KSWZ(32 * H + r32, cb)); }
;   asm volatile("s_waitcnt lgkmcnt(0)" ::: "memory"); SBAR();
;   f32x16 pb = {};
; #pragma unroll
;   for (int d0 = 0; d0 < 8; d0 += 2) {
;     pz = __builtin_amdgcn_mfma_f32_32x32x16_bf16(kf[d0], qr[d0], pz, 0, 0, 0);
;     pb = __builtin_amdgcn_mfma_f32_32x32x16_bf16(kf[d0 + 1], qr[d0 + 1], pb, 0, 0, 0); }
; #pragma unroll
;   for (int r = 0; r < 16; ++r) pz[r] += pb[r];
; }
; template <int MODE>
; __device__ __forceinline__ void nsa_single(const Params& p, const LaneId& L, int q0, int g, int ntiles, int first, char* smem, const bf16x8* qr, float gate, f32x16* o) {
;     ...
;     int pb = row, lo, hl; float badd = 0.f;
;     if (MODE == 1) { const int j = row >> 6; lo = NEG; const bool fl = ((mysel[j >> 5] >> (j & 31)) & 1u) != 0u;
;       if (row == q0) hl = fl ? (L.tq - pb) : NEG; else { hl = 1000; badd = fl ? 0.f : -INFINITY; } }
;     else { lo = L.tq - 512 - pb; hl = L.tq - pb; }
;     constexpr float C = 0.08838834764831845f * LOG2E;
;     const float A1 = L.sl2; const float B1 = L.sl2 * (float)(pb - L.tq) + A1 * (float)(4 * L.hi) + badd;
;     const int lo2 = lo - 4 * L.hi, hl2 = hl - 4 * L.hi;
;     const bool nomask = __all(lo2 < 0 && hl2 >= 63);
.LBB0_344:
	v_add_u32_e32 v163, 0xfffffe00, v161
	v_cmp_lt_i32_e32 vcc, 62, v161
	v_cmp_gt_i32_e64 s[12:13], 0, v163
	v_cvt_f32_i32_e32 v2, v162
	s_nop 3
	s_and_b64 vcc, s[12:13], vcc
	s_cmp_lg_u64 vcc, exec
	s_cselect_b64 s[98:99], -1, 0
	v_fma_f32 v2, v132, v2, v150
	v_add_u32_e32 v242, s22, v151
	v_add_u32_e32 v248, s22, v160
	v_add_u32_e32 v249, v242, v152
	ds_read_b128 v[84:87], v249
	v_add_u32_e32 v251, v242, v153
	ds_read_b128 v[88:91], v251
	v_add_u32_e32 v249, v242, v154
	ds_read_b128 v[92:95], v249
	v_add_u32_e32 v251, v242, v155
	ds_read_b128 v[96:99], v251
	v_add_u32_e32 v249, v242, v156
	ds_read_b128 v[194:197], v249
	v_add_u32_e32 v251, v242, v157
	ds_read_b128 v[198:201], v251
	v_add_u32_e32 v249, v242, v158
	ds_read_b128 v[202:205], v249
	v_add_u32_e32 v251, v242, v159
	ds_read_b128 v[206:209], v251
	v_add_f32_e32 v243, 0x41000000, v165
	v_mov_b32_e32 v250, v2
	s_waitcnt lgkmcnt(7)
	v_mfma_f32_32x32x16_bf16 v[68:83], v[84:87], v[100:103], v[226:241]
	v_add_u32_e32 v249, v242, v152
	ds_read_b128 v[84:87], v249 offset:8192
	s_waitcnt lgkmcnt(7)
	v_mfma_f32_32x32x16_bf16 v[68:83], v[88:91], v[104:107], v[68:83]
	v_add_u32_e32 v251, v242, v153
	ds_read_b128 v[88:91], v251 offset:8192
	s_waitcnt lgkmcnt(7)
	v_mfma_f32_32x32x16_bf16 v[68:83], v[92:95], v[108:111], v[68:83]
	v_add_u32_e32 v249, v242, v154
	ds_read_b128 v[92:95], v249 offset:8192
	s_waitcnt lgkmcnt(7)
	v_mfma_f32_32x32x16_bf16 v[68:83], v[96:99], v[112:115], v[68:83]
	v_add_u32_e32 v251, v242, v155
	ds_read_b128 v[96:99], v251 offset:8192
	s_waitcnt lgkmcnt(7)
	v_mfma_f32_32x32x16_bf16 v[68:83], v[194:197], v[116:119], v[68:83]
	v_add_u32_e32 v249, v242, v156
	ds_read_b128 v[194:197], v249 offset:8192
	s_waitcnt lgkmcnt(7)
	v_mfma_f32_32x32x16_bf16 v[68:83], v[198:201], v[120:123], v[68:83]
	v_add_u32_e32 v251, v242, v157
	ds_read_b128 v[198:201], v251 offset:8192
	s_waitcnt lgkmcnt(7)
	v_mfma_f32_32x32x16_bf16 v[68:83], v[202:205], v[124:127], v[68:83]
	v_add_u32_e32 v249, v242, v158
	ds_read_b128 v[202:205], v249 offset:8192
	s_waitcnt lgkmcnt(7)
	v_mfma_f32_32x32x16_bf16 v[68:83], v[206:209], v[128:131], v[68:83]
	v_add_u32_e32 v251, v242, v159
	ds_read_b128 v[206:209], v251 offset:8192
	s_waitcnt lgkmcnt(7)
	v_mfma_f32_32x32x16_bf16 v[210:225], v[84:87], v[100:103], v[226:241]
	ds_read_b64_tr_b16 v[84:85], v248 offset:0
	ds_read_b64_tr_b16 v[86:87], v248 offset:2048
	s_waitcnt lgkmcnt(8)
	v_mfma_f32_32x32x16_bf16 v[210:225], v[88:91], v[104:107], v[210:225]
	ds_read_b64_tr_b16 v[88:89], v248 offset:4096
	ds_read_b64_tr_b16 v[90:91], v248 offset:6144
	s_waitcnt lgkmcnt(9)
	v_mfma_f32_32x32x16_bf16 v[210:225], v[92:95], v[108:111], v[210:225]
	ds_read_b64_tr_b16 v[92:93], v248 offset:512
	ds_read_b64_tr_b16 v[94:95], v248 offset:2560
	s_waitcnt lgkmcnt(10)
	v_mfma_f32_32x32x16_bf16 v[210:225], v[96:99], v[112:115], v[210:225]
	ds_read_b64_tr_b16 v[96:97], v248 offset:4608
	ds_read_b64_tr_b16 v[98:99], v248 offset:6656
	s_waitcnt lgkmcnt(11)
	v_mfma_f32_32x32x16_bf16 v[210:225], v[194:197], v[116:119], v[210:225]
	ds_read_b64_tr_b16 v[194:195], v248 offset:1024
	ds_read_b64_tr_b16 v[196:197], v248 offset:3072
	s_waitcnt lgkmcnt(12)
	v_mfma_f32_32x32x16_bf16 v[210:225], v[198:201], v[120:123], v[210:225]
	ds_read_b64_tr_b16 v[198:199], v248 offset:5120
	ds_read_b64_tr_b16 v[200:201], v248 offset:7168
	s_waitcnt lgkmcnt(13)
	v_mfma_f32_32x32x16_bf16 v[210:225], v[202:205], v[124:127], v[210:225]
	ds_read_b64_tr_b16 v[202:203], v248 offset:1536
	ds_read_b64_tr_b16 v[204:205], v248 offset:3584
	s_waitcnt lgkmcnt(14)
	v_mfma_f32_32x32x16_bf16 v[210:225], v[206:209], v[128:131], v[210:225]
	ds_read_b64_tr_b16 v[206:207], v248 offset:5632
	ds_read_b64_tr_b16 v[208:209], v248 offset:7680
	v_fmamk_f32 v251, v132, 0x42000000, v2
	s_and_b64 vcc, exec, s[98:99]
	s_cbranch_vccz .Lwin_nm
	v_cmp_lt_i32_e32 vcc, -1, v161
	v_cmp_lt_i32_e64 s[10:11], 0, v161
	v_cmp_lt_i32_e64 s[12:13], 1, v161
	v_cmp_lt_i32_e64 s[2:3], 2, v161
	s_nop 0
	v_cndmask_b32_e32 v68, v183, v68, vcc
	v_cndmask_b32_e64 v69, v183, v69, s[10:11]
	v_cndmask_b32_e64 v70, v183, v70, s[12:13]
	v_cndmask_b32_e64 v71, v183, v71, s[2:3]
	v_cmp_lt_i32_e32 vcc, 7, v161
	v_cmp_lt_i32_e64 s[10:11], 8, v161
	v_cmp_lt_i32_e64 s[12:13], 9, v161
	v_cmp_lt_i32_e64 s[2:3], 10, v161
	s_nop 0
	v_cndmask_b32_e32 v72, v183, v72, vcc
	v_cndmask_b32_e64 v73, v183, v73, s[10:11]
	v_cndmask_b32_e64 v74, v183, v74, s[12:13]
	v_cndmask_b32_e64 v75, v183, v75, s[2:3]
	v_cmp_lt_i32_e32 vcc, 15, v161
	v_cmp_lt_i32_e64 s[10:11], 16, v161
	v_cmp_lt_i32_e64 s[12:13], 17, v161
	v_cmp_lt_i32_e64 s[2:3], 18, v161
	s_nop 0
	v_cndmask_b32_e32 v76, v183, v76, vcc
	v_cndmask_b32_e64 v77, v183, v77, s[10:11]
	v_cndmask_b32_e64 v78, v183, v78, s[12:13]
	v_cndmask_b32_e64 v79, v183, v79, s[2:3]
	v_cmp_lt_i32_e32 vcc, 23, v161
	v_cmp_lt_i32_e64 s[10:11], 24, v161
	v_cmp_lt_i32_e64 s[12:13], 25, v161
	v_cmp_lt_i32_e64 s[2:3], 26, v161
	s_nop 0
	v_cndmask_b32_e32 v80, v183, v80, vcc
	v_cndmask_b32_e64 v81, v183, v81, s[10:11]
	v_cndmask_b32_e64 v82, v183, v82, s[12:13]
	v_cndmask_b32_e64 v83, v183, v83, s[2:3]
	v_cmp_gt_i32_e32 vcc, 0, v163
	v_cmp_gt_i32_e64 s[10:11], 1, v163
	v_cmp_gt_i32_e64 s[12:13], 2, v163
	v_cmp_gt_i32_e64 s[2:3], 3, v163
	s_nop 0
	v_cndmask_b32_e32 v68, v183, v68, vcc
	v_cndmask_b32_e64 v69, v183, v69, s[10:11]
	v_cndmask_b32_e64 v70, v183, v70, s[12:13]
	v_cndmask_b32_e64 v71, v183, v71, s[2:3]
	v_cmp_gt_i32_e32 vcc, 8, v163
	v_cmp_gt_i32_e64 s[10:11], 9, v163
	v_cmp_gt_i32_e64 s[12:13], 10, v163
	v_cmp_gt_i32_e64 s[2:3], 11, v163
	s_nop 0
	v_cndmask_b32_e32 v72, v183, v72, vcc
	v_cndmask_b32_e64 v73, v183, v73, s[10:11]
; template <bool MASK, int H> __device__ __forceinline__ void bias_half(f32x16& pz, float C, float A1, float B1, int lo, int hl) {
; #pragma unroll
;   for (int r = 0; r < 16; ++r) {
;     const int c0 = (r & 3) + 8 * (r >> 2) + 32 * H;
;     float s0 = fmaf(pz[r], C, fmaf(A1, (float)c0, B1));
;     if (MASK) s0 = (c0 > lo && c0 <= hl) ? s0 : -INFINITY;
;     pz[r] = s0;
;   }
; }
; __device__ __forceinline__ void row_bcast(float* fac, const LaneId& L, float f, f32x4* f4) {
;   if (L.hi == 0) fac[L.r32] = f;
; #pragma unroll
;   for (int a = 0; a < 4; ++a) f4[a] = *reinterpret_cast<const f32x4*>(fac + 8 * a + 4 * L.hi);
; }
	v_cndmask_b32_e64 v74, v183, v74, s[12:13]
	v_cndmask_b32_e64 v75, v183, v75, s[2:3]
	v_cmp_gt_i32_e32 vcc, 16, v163
	v_cmp_gt_i32_e64 s[10:11], 17, v163
	v_cmp_gt_i32_e64 s[12:13], 18, v163
	v_cmp_gt_i32_e64 s[2:3], 19, v163
	s_nop 0
	v_cndmask_b32_e32 v76, v183, v76, vcc
	v_cndmask_b32_e64 v77, v183, v77, s[10:11]
	v_cndmask_b32_e64 v78, v183, v78, s[12:13]
	v_cndmask_b32_e64 v79, v183, v79, s[2:3]
	v_cmp_gt_i32_e32 vcc, 24, v163
	v_cmp_gt_i32_e64 s[10:11], 25, v163
	v_cmp_gt_i32_e64 s[12:13], 26, v163
	v_cmp_gt_i32_e64 s[2:3], 27, v163
	s_nop 0
	v_cndmask_b32_e32 v80, v183, v80, vcc
	v_cndmask_b32_e64 v81, v183, v81, s[10:11]
	v_cndmask_b32_e64 v82, v183, v82, s[12:13]
	v_cndmask_b32_e64 v83, v183, v83, s[2:3]
	v_cmp_lt_i32_e32 vcc, 31, v161
	v_cmp_lt_i32_e64 s[10:11], 32, v161
	v_cmp_lt_i32_e64 s[12:13], 33, v161
	v_cmp_lt_i32_e64 s[2:3], 34, v161
	s_nop 0
	v_cndmask_b32_e32 v210, v183, v210, vcc
	v_cndmask_b32_e64 v211, v183, v211, s[10:11]
	v_cndmask_b32_e64 v212, v183, v212, s[12:13]
	v_cndmask_b32_e64 v213, v183, v213, s[2:3]
	v_cmp_lt_i32_e32 vcc, 39, v161
	v_cmp_lt_i32_e64 s[10:11], 40, v161
	v_cmp_lt_i32_e64 s[12:13], 41, v161
	v_cmp_lt_i32_e64 s[2:3], 42, v161
	s_nop 0
	v_cndmask_b32_e32 v214, v183, v214, vcc
	v_cndmask_b32_e64 v215, v183, v215, s[10:11]
	v_cndmask_b32_e64 v216, v183, v216, s[12:13]
	v_cndmask_b32_e64 v217, v183, v217, s[2:3]
	v_cmp_lt_i32_e32 vcc, 47, v161
	v_cmp_lt_i32_e64 s[10:11], 48, v161
	v_cmp_lt_i32_e64 s[12:13], 49, v161
	v_cmp_lt_i32_e64 s[2:3], 50, v161
	s_nop 0
	v_cndmask_b32_e32 v218, v183, v218, vcc
	v_cndmask_b32_e64 v219, v183, v219, s[10:11]
	v_cndmask_b32_e64 v220, v183, v220, s[12:13]
	v_cndmask_b32_e64 v221, v183, v221, s[2:3]
	v_cmp_lt_i32_e32 vcc, 55, v161
	v_cmp_lt_i32_e64 s[10:11], 56, v161
	v_cmp_lt_i32_e64 s[12:13], 57, v161
	v_cmp_lt_i32_e64 s[2:3], 58, v161
	s_nop 0
	v_cndmask_b32_e32 v222, v183, v222, vcc
	v_cndmask_b32_e64 v223, v183, v223, s[10:11]
	v_cndmask_b32_e64 v224, v183, v224, s[12:13]
	v_cndmask_b32_e64 v225, v183, v225, s[2:3]
	v_cmp_gt_i32_e32 vcc, 32, v163
	v_cmp_gt_i32_e64 s[10:11], 33, v163
	v_cmp_gt_i32_e64 s[12:13], 34, v163
	v_cmp_gt_i32_e64 s[2:3], 35, v163
	s_nop 0
	v_cndmask_b32_e32 v210, v183, v210, vcc
	v_cndmask_b32_e64 v211, v183, v211, s[10:11]
	v_cndmask_b32_e64 v212, v183, v212, s[12:13]
	v_cndmask_b32_e64 v213, v183, v213, s[2:3]
	v_cmp_gt_i32_e32 vcc, 40, v163
	v_cmp_gt_i32_e64 s[10:11], 41, v163
	v_cmp_gt_i32_e64 s[12:13], 42, v163
	v_cmp_gt_i32_e64 s[2:3], 43, v163
	s_nop 0
	v_cndmask_b32_e32 v214, v183, v214, vcc
	v_cndmask_b32_e64 v215, v183, v215, s[10:11]
	v_cndmask_b32_e64 v216, v183, v216, s[12:13]
	v_cndmask_b32_e64 v217, v183, v217, s[2:3]
	v_cmp_gt_i32_e32 vcc, 48, v163
	v_cmp_gt_i32_e64 s[10:11], 49, v163
	v_cmp_gt_i32_e64 s[12:13], 50, v163
	v_cmp_gt_i32_e64 s[2:3], 51, v163
	s_nop 0
	v_cndmask_b32_e32 v218, v183, v218, vcc
	v_cndmask_b32_e64 v219, v183, v219, s[10:11]
	v_cndmask_b32_e64 v220, v183, v220, s[12:13]
	v_cndmask_b32_e64 v221, v183, v221, s[2:3]
	v_cmp_gt_i32_e32 vcc, 56, v163
	v_cmp_gt_i32_e64 s[10:11], 57, v163
	v_cmp_gt_i32_e64 s[12:13], 58, v163
	v_cmp_gt_i32_e64 s[2:3], 59, v163
	s_nop 0
	v_cndmask_b32_e32 v222, v183, v222, vcc
	v_cndmask_b32_e64 v223, v183, v223, s[10:11]
	v_cndmask_b32_e64 v224, v183, v224, s[12:13]
	v_cndmask_b32_e64 v225, v183, v225, s[2:3]
.Lwin_nm:
	v_max3_f32 v244, v68, v69, v70
	v_max3_f32 v244, v244, v71, v72
	v_max3_f32 v244, v244, v73, v74
	v_max3_f32 v244, v244, v75, v76
	v_max3_f32 v244, v244, v77, v78
	v_max3_f32 v244, v244, v79, v80
	v_max3_f32 v244, v244, v81, v82
	v_max_f32_e32 v244, v244, v83
	v_fmamk_f32 v246, v244, 0x3e0293ee, v250
	s_nop 1
	v_max3_f32 v244, v210, v211, v212
	v_max3_f32 v244, v244, v213, v214
	v_max3_f32 v244, v244, v215, v216
	v_max3_f32 v244, v244, v217, v218
	v_max3_f32 v244, v244, v219, v220
	v_max3_f32 v244, v244, v221, v222
	v_max3_f32 v244, v244, v223, v224
	v_max_f32_e32 v244, v244, v225
	v_fmamk_f32 v245, v244, 0x3e0293ee, v251
	v_max_f32_e32 v246, v246, v245
	v_mov_b32_e32 v245, v246
	s_nop 1
	v_permlane32_swap_b32_e32 v246, v245
	v_max_f32_e32 v246, v246, v245
	v_cmp_gt_f32_e32 vcc, v246, v243
	s_cbranch_vccz .Lwin_nr
	v_max_f32_e32 v246, v246, v165
	v_sub_f32_e32 v247, v165, v246
	v_exp_f32_e32 v247, v247
	v_mov_b32_e32 v165, v246
	s_and_saveexec_b64 s[2:3], s[8:9]
	ds_write_b32 v148, v247
	s_or_b64 exec, exec, s[2:3]
	v_mul_f32_e32 v143, v143, v247
	ds_read_b128 v[168:171], v147 offset:0
	ds_read_b128 v[172:175], v147 offset:32
	s_waitcnt lgkmcnt(0)
	v_mul_f32_e32 v52, v52, v168
	v_mul_f32_e32 v53, v53, v169
	v_mul_f32_e32 v54, v54, v170
	v_mul_f32_e32 v55, v55, v171
	v_mul_f32_e32 v56, v56, v172
	v_mul_f32_e32 v57, v57, v173
	v_mul_f32_e32 v58, v58, v174
	v_mul_f32_e32 v59, v59, v175
	v_mul_f32_e32 v36, v36, v168
	v_mul_f32_e32 v37, v37, v169
	v_mul_f32_e32 v38, v38, v170
	v_mul_f32_e32 v39, v39, v171
	v_mul_f32_e32 v40, v40, v172
	v_mul_f32_e32 v41, v41, v173
	v_mul_f32_e32 v42, v42, v174
	v_mul_f32_e32 v43, v43, v175
	v_mul_f32_e32 v20, v20, v168
	v_mul_f32_e32 v21, v21, v169
	v_mul_f32_e32 v22, v22, v170
	v_mul_f32_e32 v23, v23, v171
	v_mul_f32_e32 v24, v24, v172
	v_mul_f32_e32 v25, v25, v173
	v_mul_f32_e32 v26, v26, v174
	v_mul_f32_e32 v27, v27, v175
	v_mul_f32_e32 v4, v4, v168
	v_mul_f32_e32 v5, v5, v169
	v_mul_f32_e32 v6, v6, v170
	v_mul_f32_e32 v7, v7, v171
	v_mul_f32_e32 v8, v8, v172
	v_mul_f32_e32 v9, v9, v173
	v_mul_f32_e32 v10, v10, v174
	v_mul_f32_e32 v11, v11, v175
	ds_read_b128 v[168:171], v147 offset:64
	ds_read_b128 v[172:175], v147 offset:96
	s_waitcnt lgkmcnt(0)
	v_mul_f32_e32 v60, v60, v168
	v_mul_f32_e32 v61, v61, v169
	v_mul_f32_e32 v62, v62, v170
	v_mul_f32_e32 v63, v63, v171
	v_mul_f32_e32 v64, v64, v172
	v_mul_f32_e32 v65, v65, v173
	v_mul_f32_e32 v66, v66, v174
	v_mul_f32_e32 v67, v67, v175
	v_mul_f32_e32 v44, v44, v168
	v_mul_f32_e32 v45, v45, v169
	v_mul_f32_e32 v46, v46, v170
	v_mul_f32_e32 v47, v47, v171
	v_mul_f32_e32 v48, v48, v172
	v_mul_f32_e32 v49, v49, v173
	v_mul_f32_e32 v50, v50, v174
	v_mul_f32_e32 v51, v51, v175
	v_mul_f32_e32 v28, v28, v168
	v_mul_f32_e32 v29, v29, v169
	v_mul_f32_e32 v30, v30, v170
	v_mul_f32_e32 v31, v31, v171
	v_mul_f32_e32 v32, v32, v172
	v_mul_f32_e32 v33, v33, v173
	v_mul_f32_e32 v34, v34, v174
	v_mul_f32_e32 v35, v35, v175
	v_mul_f32_e32 v12, v12, v168
	v_mul_f32_e32 v13, v13, v169
	v_mul_f32_e32 v14, v14, v170
	v_mul_f32_e32 v15, v15, v171
	v_mul_f32_e32 v16, v16, v172
	v_mul_f32_e32 v17, v17, v173
	v_mul_f32_e32 v18, v18, v174
	v_mul_f32_e32 v19, v19, v175
; #define SBAR() __builtin_amdgcn_sched_barrier(0)
; #define TRQ(D0) const s16x4 l0_##D0 = tr_read<v_rd_off(D0, 2 * H, 0)>(vb), h0_##D0 = tr_read<v_rd_off(D0, 2 * H, 1)>(vb), \
;                             l1_##D0 = tr_read<v_rd_off(D0, 2 * H + 1, 0)>(vb), h1_##D0 = tr_read<v_rd_off(D0, 2 * H + 1, 1)>(vb)
; template <int H> __device__ __forceinline__ void pv_half(f32x16* o, int vb, bf16x8 paA, bf16x8 paB) {
;     ...
;   TRQ(0); TRQ(1); TRQ(2); TRQ(3);
;     ...
;   asm volatile("s_waitcnt lgkmcnt(0)" ::: "memory"); SBAR();
;     ...
;   o[0] = __builtin_amdgcn_mfma_f32_32x32x16_bf16(paA, PK(l0_0, h0_0), o[0], 0, 0, 0);
;   o[1] = __builtin_amdgcn_mfma_f32_32x32x16_bf16(paA, PK(l0_1, h0_1), o[1], 0, 0, 0);
;   o[2] = __builtin_amdgcn_mfma_f32_32x32x16_bf16(paA, PK(l0_2, h0_2), o[2], 0, 0, 0);
;   o[3] = __builtin_amdgcn_mfma_f32_32x32x16_bf16(paA, PK(l0_3, h0_3), o[3], 0, 0, 0);
;   o[0] = __builtin_amdgcn_mfma_f32_32x32x16_bf16(paB, PK(l1_0, h1_0), o[0], 0, 0, 0);
;   o[1] = __builtin_amdgcn_mfma_f32_32x32x16_bf16(paB, PK(l1_1, h1_1), o[1], 0, 0, 0);
;   o[2] = __builtin_amdgcn_mfma_f32_32x32x16_bf16(paB, PK(l1_2, h1_2), o[2], 0, 0, 0);
;   o[3] = __builtin_amdgcn_mfma_f32_32x32x16_bf16(paB, PK(l1_3, h1_3), o[3], 0, 0, 0);
;     ...
; }
; template <int MODE>
; __device__ __forceinline__ void nsa_single(const Params& p, const LaneId& L, int q0, int g, int ntiles, int first, char* smem, const bf16x8* qr, float gate, f32x16* o) {
;     ...
;     NSA_SHALF(0);
;     NSA_SHALF(1);
;     ...
;   }
.Lwin_nr:
	v_sub_f32_e32 v242, v250, v165
	v_sub_f32_e32 v249, v251, v165
	s_nop 0
	v_fmamk_f32 v68, v68, 0x3e0293ee, v242
	v_fmamk_f32 v69, v69, 0x3e0293ee, v242
	v_fmamk_f32 v70, v70, 0x3e0293ee, v242
	v_fmamk_f32 v71, v71, 0x3e0293ee, v242
	v_fmamk_f32 v72, v72, 0x3e0293ee, v242
	v_fmamk_f32 v73, v73, 0x3e0293ee, v242
	v_fmamk_f32 v74, v74, 0x3e0293ee, v242
	v_fmamk_f32 v75, v75, 0x3e0293ee, v242
	v_fmamk_f32 v76, v76, 0x3e0293ee, v242
	v_fmamk_f32 v77, v77, 0x3e0293ee, v242
	v_fmamk_f32 v78, v78, 0x3e0293ee, v242
	v_fmamk_f32 v79, v79, 0x3e0293ee, v242
	v_fmamk_f32 v80, v80, 0x3e0293ee, v242
	v_fmamk_f32 v81, v81, 0x3e0293ee, v242
	v_fmamk_f32 v82, v82, 0x3e0293ee, v242
	v_fmamk_f32 v83, v83, 0x3e0293ee, v242
	v_exp_f32_e32 v68, v68
	v_exp_f32_e32 v69, v69
	v_exp_f32_e32 v70, v70
	v_exp_f32_e32 v71, v71
	v_exp_f32_e32 v72, v72
	v_exp_f32_e32 v73, v73
	v_exp_f32_e32 v74, v74
	v_exp_f32_e32 v75, v75
	v_exp_f32_e32 v76, v76
	v_exp_f32_e32 v77, v77
	v_exp_f32_e32 v78, v78
	v_exp_f32_e32 v79, v79
	v_exp_f32_e32 v80, v80
	v_exp_f32_e32 v81, v81
	v_exp_f32_e32 v82, v82
	v_exp_f32_e32 v83, v83
	v_fmamk_f32 v210, v210, 0x3e0293ee, v249
	v_fmamk_f32 v211, v211, 0x3e0293ee, v249
	v_fmamk_f32 v212, v212, 0x3e0293ee, v249
	v_fmamk_f32 v213, v213, 0x3e0293ee, v249
	v_fmamk_f32 v214, v214, 0x3e0293ee, v249
	v_fmamk_f32 v215, v215, 0x3e0293ee, v249
	v_fmamk_f32 v216, v216, 0x3e0293ee, v249
	v_fmamk_f32 v217, v217, 0x3e0293ee, v249
	v_fmamk_f32 v218, v218, 0x3e0293ee, v249
	v_fmamk_f32 v219, v219, 0x3e0293ee, v249
	v_fmamk_f32 v220, v220, 0x3e0293ee, v249
	v_fmamk_f32 v221, v221, 0x3e0293ee, v249
	v_fmamk_f32 v222, v222, 0x3e0293ee, v249
	v_fmamk_f32 v223, v223, 0x3e0293ee, v249
	v_fmamk_f32 v224, v224, 0x3e0293ee, v249
	v_fmamk_f32 v225, v225, 0x3e0293ee, v249
	v_add_f32_e32 v246, v68, v69
	v_add_f32_e32 v247, v70, v71
	v_add_f32_e32 v246, v246, v72
	v_add_f32_e32 v246, v246, v73
	v_add_f32_e32 v247, v247, v74
	v_add_f32_e32 v247, v247, v75
	v_add_f32_e32 v246, v246, v76
	v_add_f32_e32 v246, v246, v77
	v_add_f32_e32 v247, v247, v78
	v_add_f32_e32 v247, v247, v79
	v_add_f32_e32 v246, v246, v80
	v_add_f32_e32 v246, v246, v81
	v_add_f32_e32 v247, v247, v82
	v_add_f32_e32 v247, v247, v83
	v_cvt_pk_bf16_f32 v168, v68, v69
	v_cvt_pk_bf16_f32 v169, v70, v71
	v_cvt_pk_bf16_f32 v170, v72, v73
	v_cvt_pk_bf16_f32 v171, v74, v75
	v_cvt_pk_bf16_f32 v172, v76, v77
	v_cvt_pk_bf16_f32 v173, v78, v79
	v_cvt_pk_bf16_f32 v174, v80, v81
	v_cvt_pk_bf16_f32 v175, v82, v83
	v_exp_f32_e32 v210, v210
	v_exp_f32_e32 v211, v211
	v_exp_f32_e32 v212, v212
	v_exp_f32_e32 v213, v213
	v_exp_f32_e32 v214, v214
	v_exp_f32_e32 v215, v215
	v_exp_f32_e32 v216, v216
	v_exp_f32_e32 v217, v217
	v_exp_f32_e32 v218, v218
	v_exp_f32_e32 v219, v219
	v_exp_f32_e32 v220, v220
	v_exp_f32_e32 v221, v221
	v_exp_f32_e32 v222, v222
	v_exp_f32_e32 v223, v223
	v_exp_f32_e32 v224, v224
	v_exp_f32_e32 v225, v225
	v_permlane32_swap_b32_e32 v168, v170
	v_permlane32_swap_b32_e32 v169, v171
	v_permlane32_swap_b32_e32 v172, v174
	v_permlane32_swap_b32_e32 v173, v175
	v_add_f32_e32 v246, v246, v210
	v_add_f32_e32 v246, v246, v211
	v_add_f32_e32 v247, v247, v212
	v_add_f32_e32 v247, v247, v213
	v_add_f32_e32 v246, v246, v214
	v_add_f32_e32 v246, v246, v215
	v_add_f32_e32 v247, v247, v216
	v_add_f32_e32 v247, v247, v217
	v_add_f32_e32 v246, v246, v218
	v_add_f32_e32 v246, v246, v219
	v_add_f32_e32 v247, v247, v220
	v_add_f32_e32 v247, v247, v221
	v_add_f32_e32 v246, v246, v222
	v_add_f32_e32 v246, v246, v223
	v_add_f32_e32 v247, v247, v224
	v_add_f32_e32 v247, v247, v225
	v_add_f32_e32 v246, v246, v247
	v_add_f32_e32 v143, v143, v246
	v_cvt_pk_bf16_f32 v68, v210, v211
	v_cvt_pk_bf16_f32 v69, v212, v213
	v_cvt_pk_bf16_f32 v70, v214, v215
	v_cvt_pk_bf16_f32 v71, v216, v217
	v_cvt_pk_bf16_f32 v72, v218, v219
	v_cvt_pk_bf16_f32 v73, v220, v221
	v_cvt_pk_bf16_f32 v74, v222, v223
	v_cvt_pk_bf16_f32 v75, v224, v225
	s_waitcnt lgkmcnt(0)
	s_nop 0
	v_permlane32_swap_b32_e32 v68, v70
	v_permlane32_swap_b32_e32 v69, v71
	v_permlane32_swap_b32_e32 v72, v74
	v_permlane32_swap_b32_e32 v73, v75
	s_nop 1
	v_mfma_f32_32x32x16_bf16 v[52:67], v[168:171], v[84:87], v[52:67]
	ds_read_b64_tr_b16 v[84:85], v248 offset:8192
	ds_read_b64_tr_b16 v[86:87], v248 offset:10240
	v_mfma_f32_32x32x16_bf16 v[36:51], v[168:171], v[92:95], v[36:51]
	ds_read_b64_tr_b16 v[92:93], v248 offset:8704
	ds_read_b64_tr_b16 v[94:95], v248 offset:10752
	v_mfma_f32_32x32x16_bf16 v[20:35], v[168:171], v[194:197], v[20:35]
	ds_read_b64_tr_b16 v[194:195], v248 offset:9216
	ds_read_b64_tr_b16 v[196:197], v248 offset:11264
	v_mfma_f32_32x32x16_bf16 v[4:19], v[168:171], v[202:205], v[4:19]
	ds_read_b64_tr_b16 v[202:203], v248 offset:9728
	ds_read_b64_tr_b16 v[204:205], v248 offset:11776
	v_mfma_f32_32x32x16_bf16 v[52:67], v[172:175], v[88:91], v[52:67]
	ds_read_b64_tr_b16 v[88:89], v248 offset:12288
	ds_read_b64_tr_b16 v[90:91], v248 offset:14336
	v_mfma_f32_32x32x16_bf16 v[36:51], v[172:175], v[96:99], v[36:51]
	ds_read_b64_tr_b16 v[96:97], v248 offset:12800
	ds_read_b64_tr_b16 v[98:99], v248 offset:14848
	v_mfma_f32_32x32x16_bf16 v[20:35], v[172:175], v[198:201], v[20:35]
	ds_read_b64_tr_b16 v[198:199], v248 offset:13312
	ds_read_b64_tr_b16 v[200:201], v248 offset:15360
	v_mfma_f32_32x32x16_bf16 v[4:19], v[172:175], v[206:209], v[4:19]
	ds_read_b64_tr_b16 v[206:207], v248 offset:13824
	ds_read_b64_tr_b16 v[208:209], v248 offset:15872
	s_waitcnt lgkmcnt(14)
	v_mfma_f32_32x32x16_bf16 v[52:67], v[68:71], v[84:87], v[52:67]
	s_waitcnt lgkmcnt(12)
	v_mfma_f32_32x32x16_bf16 v[36:51], v[68:71], v[92:95], v[36:51]
	s_waitcnt lgkmcnt(10)
	v_mfma_f32_32x32x16_bf16 v[20:35], v[68:71], v[194:197], v[20:35]
	s_waitcnt lgkmcnt(8)
	v_mfma_f32_32x32x16_bf16 v[4:19], v[68:71], v[202:205], v[4:19]
	s_waitcnt lgkmcnt(6)
	v_mfma_f32_32x32x16_bf16 v[52:67], v[72:75], v[88:91], v[52:67]
	s_waitcnt lgkmcnt(4)
	v_mfma_f32_32x32x16_bf16 v[36:51], v[72:75], v[96:99], v[36:51]
	s_waitcnt lgkmcnt(2)
	v_mfma_f32_32x32x16_bf16 v[20:35], v[72:75], v[198:201], v[20:35]
	s_waitcnt lgkmcnt(0)
	v_mfma_f32_32x32x16_bf16 v[4:19], v[72:75], v[206:209], v[4:19]
	s_addk_i32 s1, 0x4000
	s_add_i32 s0, s0, 1
	v_lshl_add_u64 v[134:135], v[134:135], 0, s[20:21]
	v_lshl_add_u64 v[136:137], v[136:137], 0, s[20:21]
	v_lshl_add_u64 v[138:139], v[138:139], 0, s[20:21]
	v_lshl_add_u64 v[140:141], v[140:141], 0, s[20:21]
	v_add_u32_e32 v161, 64, v161
	v_subrev_u32_e32 v162, 64, v162
	s_cmp_eq_u32 s24, s1
	s_cbranch_scc1 .LBB0_361
	s_branch .LBB0_342
